# attention: snake unit order (jh Gray code) so each unit shares window rows or the column band with its predecessor; DMA pieces that the next unit re-reads keep default policy, others nt
# speedup vs baseline: 1.0120x; 1.0120x over previous
; template <int KIND> __device__ __forceinline__ void attn_dma(unsigned dst, const bf16_t* src, const AttnUnit& u, int wid, int lane) {
;     const int np = u.nrows * 5;
;     const char* base = (const char*)(src + ((size_t)(u.b * NHEAD + u.h) * SEQ + u.krow_lo * 64 + 24 * u.jh) * HD);
; #pragma unroll
;     for (int it = 0; it < 10; ++it) {
;         const int pi = it * 8 + wid;
;         if (pi < np) {
; __device__ __forceinline__ void p2_attention(Frame& F, const bf16_t* Qg, const bf16_t* Kg, const bf16_t* Vg, bf16_t* MIX) {
;     ...
;             attn_dma<1>(lds0 + AT_B, Vg, u, wid, lane);
.LBB0_285:
	s_lshl_b32 s0, s92, 3
	s_or_b32 s6, s0, s89
	s_ashr_i32 s7, s6, 31
	s_lshl_b64 s[6:7], s[6:7], 12
	v_lshlrev_b32_e32 v96, 6, v188
	v_lshl_add_u64 v[16:17], s[6:7], 0, v[96:97]
	s_mul_i32 s0, s95, 24
	v_or_b32_e32 v16, s0, v16
	s_mul_i32 s1, s91, 5
	v_lshlrev_b64 v[16:17], 7, v[16:17]
	s_lshl_b32 s101, s95, 4
	s_lshr_b32 s101, s100, s101
	s_bitcmp1_b32 s93, 0
	s_cselect_b32 s101, 0x3e0, s101
	s_cmp_ge_i32 s85, s1
	v_lshl_add_u64 v[16:17], s[22:23], 0, v[16:17]
	s_waitcnt vmcnt(2)
	s_cbranch_scc0 .LBB0_307
	s_cmp_ge_i32 s43, s1
	s_cbranch_scc0 .LBB0_308

; #define LAS __attribute__((address_space(3)))
; __device__ __forceinline__ void p2_attention(Frame& F, const bf16_t* Qg, const bf16_t* Kg, const bf16_t* Vg, bf16_t* MIX) {
;     ...
;             const int r = u.r0 + wid, rs = rs_of(r), wbase = rs - u.krow_lo;
;             u32x4 pw[2][8]; float il[2];
; #pragma unroll
;             for (int jb = 0; jb < 2; ++jb) {
;                 const int o = 8 * jb, kcol0 = 24 * u.jh + o, cq = 32 * u.jh + 16 * jb + q;
;                 int cs = cq - 8; cs = cs < 0 ? 0 : cs; cs = cs > 48 ? 48 : cs;
;                 f32x4 sc[8][2];
;                 {
;                     const int fk = ((q >> 1) & 1) | (((jb + (q >> 2)) & 3) << 1), x0 = g ^ fk;
;                     const LAS unsigned char* ka = lds + AT_A + (wbase * 40 + o + 8 * (q >> 2) + (q & 3)) * 128;
;                     const LAS unsigned char* k0p = ka + x0 * 16;
;                     const LAS unsigned char* k1p = ka + (x0 ^ 4) * 16;
; #pragma unroll
;                     for (int wl = 0; wl < 8; ++wl)
; #pragma unroll
;                         for (int blk = 0; blk < 2; ++blk) {
;                             const bf16x8 k0 = *(const LAS bf16x8*)(k0p + wl * 5120 + blk * 512), k1 = *(const LAS bf16x8*)(k1p + wl * 5120 + blk * 512);
;                             f32x4 a = (f32x4){0.f, 0.f, 0.f, 0.f};
;                             a = __builtin_amdgcn_mfma_f32_16x16x32_bf16(k0, qf[jb][0], a, 0, 0, 0);
;                             a = __builtin_amdgcn_mfma_f32_16x16x32_bf16(k1, qf[jb][1], a, 0, 0, 0);
;                             sc[wl][blk] = a;
;                         }
;                 }
;                 const LAS float* tab = (const LAS float*)(lds + AT_TAB) + (rs - r + 7) * 64 + 16 + (kcol0 - cq + 15) + 8 * g;
;                 const int voff = kcol0 + 8 * g - cs;
;                 float mx = -INFINITY;
; #pragma unroll
;                 for (int wl = 0; wl < 8; ++wl)
; #pragma unroll
;                     for (int blk = 0; blk < 2; ++blk)
; #pragma unroll
;                         for (int e = 0; e < 4; ++e) {
;                             const int ep = 4 * blk + e;
;                             float s_ = sc[wl][blk][e] + tab[wl * 64 + ep];
;                             s_ = ((unsigned)(voff + ep) < 16u) ? s_ : -INFINITY;
;                             sc[wl][blk][e] = s_; mx = fmaxf(mx, s_);
.LBB0_296:
	s_add_i32 s96, s90, s85
	v_med3_i32 v16, s96, 4, 60
	v_add_u32_e32 v54, -4, v16
	v_sub_u32_e32 v16, v54, v188
	v_mul_lo_u32 v96, v16, 40
	v_add_u32_e32 v16, v165, v96
	v_lshl_add_u32 v49, v16, 7, 0
	v_add_u32_e32 v94, v49, v171
	v_add_u32_e32 v95, v49, v172
	ds_read_b128 v[16:19], v94
	ds_read_b128 v[20:23], v94 offset:512
	ds_read_b128 v[24:27], v94 offset:5120
	ds_read_b128 v[28:31], v95
	ds_read_b128 v[32:35], v94 offset:5632
	ds_read_b128 v[36:39], v95 offset:512
	s_waitcnt lgkmcnt(5)
	v_mfma_f32_16x16x32_bf16 v[16:19], v[16:19], v[0:3], 0
	s_lshl_b32 s97, s95, 5
	v_or_b32_e32 v48, s97, v98
	v_max_i32_e32 v191, 8, v48
	s_waitcnt lgkmcnt(4)
	v_mfma_f32_16x16x32_bf16 v[20:23], v[20:23], v[0:3], 0
	v_add_u32_e32 v190, s0, v170
	v_sub_u32_e32 v191, v190, v191
	v_cmp_gt_u32_e32 vcc, 16, v191
	s_waitcnt lgkmcnt(3)
	v_mfma_f32_16x16x32_bf16 v[24:27], v[24:27], v[0:3], 0
	v_add_u32_e32 v251, v49, v173
	v_add_u32_e32 v49, v49, v174
	s_cmp_eq_u32 s93, -1
	s_waitcnt lgkmcnt(2)
	v_mfma_f32_16x16x32_bf16 v[16:19], v[28:31], v[4:7], v[16:19]
	s_waitcnt lgkmcnt(0)
	v_mfma_f32_16x16x32_bf16 v[20:23], v[36:39], v[4:7], v[20:23]
	ds_read_b128 v[28:31], v95 offset:5120
	ds_read_b128 v[36:39], v95 offset:5632
	s_waitcnt lgkmcnt(1)
	v_mfma_f32_16x16x32_bf16 v[40:43], v[28:31], v[4:7], v[24:27]
	ds_read_b128 v[28:31], v94 offset:10240
	v_mfma_f32_16x16x32_bf16 v[24:27], v[32:35], v[0:3], 0
	s_waitcnt lgkmcnt(1)
	v_mfma_f32_16x16x32_bf16 v[36:39], v[36:39], v[4:7], v[24:27]
	s_nop 5
	ds_read_b128 v[24:27], v95 offset:10240
	ds_read_b128 v[32:35], v94 offset:10752
	ds_read_b128 v[44:47], v95 offset:10752
	s_waitcnt lgkmcnt(3)
	v_mfma_f32_16x16x32_bf16 v[28:31], v[28:31], v[0:3], 0
	s_waitcnt lgkmcnt(2)
	v_mfma_f32_16x16x32_bf16 v[50:53], v[24:27], v[4:7], v[28:31]
	v_subrev_u32_e32 v24, s96, v54
	v_lshl_add_u32 v189, v24, 8, v169
	s_waitcnt lgkmcnt(1)
	v_mfma_f32_16x16x32_bf16 v[24:27], v[32:35], v[0:3], 0
	s_nop 1
	ds_read_b128 v[28:31], v94 offset:15360
	ds_read_b128 v[32:35], v94 offset:15872
	ds_read_b128 v[54:57], v95 offset:15360
	ds_read_b128 v[58:61], v95 offset:15872
	s_waitcnt lgkmcnt(2)
	v_mfma_f32_16x16x32_bf16 v[32:35], v[32:35], v[0:3], 0
	v_mfma_f32_16x16x32_bf16 v[44:47], v[44:47], v[4:7], v[24:27]
	s_nop 2
	ds_read_b128 v[24:27], v94 offset:20480
	ds_read_b128 v[62:65], v94 offset:20992
	ds_read_b128 v[66:69], v95 offset:20480
	ds_read_b128 v[70:73], v95 offset:20992
	ds_read_b128 v[74:77], v94 offset:25600
	ds_read_b128 v[78:81], v94 offset:26112
	ds_read_b128 v[82:85], v95 offset:25600
	ds_read_b128 v[86:89], v95 offset:26112
	v_mfma_f32_16x16x32_bf16 v[28:31], v[28:31], v[0:3], 0
	s_waitcnt lgkmcnt(8)
	v_mfma_f32_16x16x32_bf16 v[58:61], v[58:61], v[4:7], v[32:35]
	s_nop 2
	v_sub_u32_e32 v32, s0, v48
	s_waitcnt lgkmcnt(7)
	v_mfma_f32_16x16x32_bf16 v[24:27], v[24:27], v[0:3], 0
	v_lshl_add_u32 v218, v32, 2, v189
	v_add_u32_e32 v32, 0x77c, v218
	v_add_u32_e32 v34, 0x784, v218
	v_mfma_f32_16x16x32_bf16 v[54:57], v[54:57], v[4:7], v[28:31]
	s_nop 2
	ds_read_b128 v[28:31], v94 offset:30720
	ds_read_b128 v[90:93], v94 offset:31232
	ds_read_b128 v[192:195], v95 offset:30720
	ds_read_b128 v[196:199], v95 offset:31232
	ds_read_b128 v[200:203], v94 offset:35840
	ds_read_b128 v[204:207], v94 offset:36352
	ds_read_b128 v[208:211], v95 offset:35840
	ds_read_b128 v[212:215], v95 offset:36352
	ds_read2_b32 v[32:33], v32 offset1:1
	s_waitcnt lgkmcnt(14)
	v_mfma_f32_16x16x32_bf16 v[66:69], v[66:69], v[4:7], v[24:27]
	v_add_u32_e32 v94, 0x78c, v218
	v_add_u32_e32 v216, 0x794, v218
	ds_read2_b32 v[34:35], v34 offset1:1
	ds_read2_b32 v[94:95], v94 offset1:1
	ds_read2_b32 v[216:217], v216 offset1:1
	v_mfma_f32_16x16x32_bf16 v[24:27], v[62:65], v[0:3], 0
	s_waitcnt lgkmcnt(3)
	v_add_f32_e32 v16, v16, v32
	v_cndmask_b32_e32 v219, v187, v16, vcc
	v_add_f32_e32 v16, v17, v33
	v_mfma_f32_16x16x32_bf16 v[62:65], v[70:73], v[4:7], v[24:27]
	v_add_u32_e32 v17, 1, v191
	v_cmp_gt_u32_e64 s[6:7], 16, v17
	v_add_u32_e32 v17, 2, v191
	v_mfma_f32_16x16x32_bf16 v[24:27], v[74:77], v[0:3], 0
	v_cndmask_b32_e64 v220, v187, v16, s[6:7]
	s_waitcnt lgkmcnt(2)
	v_add_f32_e32 v16, v18, v34
	v_cmp_gt_u32_e64 s[8:9], 16, v17
	v_add_u32_e32 v17, 3, v191
	v_mfma_f32_16x16x32_bf16 v[70:73], v[82:85], v[4:7], v[24:27]
	v_cndmask_b32_e64 v82, v187, v16, s[8:9]
	v_add_f32_e32 v16, v19, v35
	v_cmp_gt_u32_e64 s[10:11], 16, v17
	v_mfma_f32_16x16x32_bf16 v[24:27], v[78:81], v[0:3], 0
	s_waitcnt lgkmcnt(1)
	v_add_f32_e32 v20, v20, v94
	v_cndmask_b32_e64 v83, v187, v16, s[10:11]
	v_max3_f32 v74, v219, s88, v220
	v_mfma_f32_16x16x32_bf16 v[16:19], v[28:31], v[0:3], 0
	s_waitcnt lgkmcnt(0)
	v_add_f32_e32 v75, v23, v217
	v_max3_f32 v74, v74, v82, v83
	v_add_u32_e32 v76, 0x884, v218
	v_mfma_f32_16x16x32_bf16 v[28:31], v[192:195], v[4:7], v[16:19]
	v_add_u32_e32 v78, 0x88c, v218
	v_add_u32_e32 v80, 0x894, v218
	v_mfma_f32_16x16x32_bf16 v[16:19], v[90:93], v[0:3], 0
	v_mfma_f32_16x16x32_bf16 v[32:35], v[86:89], v[4:7], v[24:27]
	s_nop 2
	v_add_u32_e32 v24, 4, v191
	v_cmp_gt_u32_e64 s[12:13], 16, v24
	v_mfma_f32_16x16x32_bf16 v[24:27], v[196:199], v[4:7], v[16:19]
	s_nop 0
	v_cndmask_b32_e64 v84, v187, v20, s[12:13]
	v_add_f32_e32 v20, v21, v95
	v_mfma_f32_16x16x32_bf16 v[16:19], v[200:203], v[0:3], 0
	v_add_u32_e32 v21, 5, v191
	v_cmp_gt_u32_e64 s[14:15], 16, v21
	v_add_u32_e32 v21, 6, v191
	v_cmp_gt_u32_e64 s[16:17], 16, v21
	v_cndmask_b32_e64 v85, v187, v20, s[14:15]
	v_add_f32_e32 v20, v22, v216
	v_cndmask_b32_e64 v86, v187, v20, s[16:17]
	v_mfma_f32_16x16x32_bf16 v[20:23], v[208:211], v[4:7], v[16:19]
	v_max3_f32 v74, v74, v84, v85
	s_nop 1
	v_add_u32_e32 v16, 7, v191
	v_cmp_gt_u32_e64 s[18:19], 16, v16
	v_mfma_f32_16x16x32_bf16 v[16:19], v[204:207], v[0:3], 0
	s_nop 0
	v_cndmask_b32_e64 v87, v187, v75, s[18:19]
	v_max3_f32 v88, v74, v86, v87
	v_add_u32_e32 v74, 0x87c, v218
	ds_read2_b32 v[74:75], v74 offset1:1
	ds_read2_b32 v[76:77], v76 offset1:1
	ds_read2_b32 v[78:79], v78 offset1:1
	ds_read2_b32 v[80:81], v80 offset1:1
	v_mfma_f32_16x16x32_bf16 v[16:19], v[212:215], v[4:7], v[16:19]
	s_waitcnt lgkmcnt(3)
; #define LAS __attribute__((address_space(3)))
; __device__ __forceinline__ void p2_attention(Frame& F, const bf16_t* Qg, const bf16_t* Kg, const bf16_t* Vg, bf16_t* MIX) {
;     ...
;                 const LAS float* tab = (const LAS float*)(lds + AT_TAB) + (rs - r + 7) * 64 + 16 + (kcol0 - cq + 15) + 8 * g;
;                 const int voff = kcol0 + 8 * g - cs;
;                 float mx = -INFINITY;
; #pragma unroll
;                 for (int wl = 0; wl < 8; ++wl)
; #pragma unroll
;                     for (int blk = 0; blk < 2; ++blk)
; #pragma unroll
;                         for (int e = 0; e < 4; ++e) {
;                             const int ep = 4 * blk + e;
;                             float s_ = sc[wl][blk][e] + tab[wl * 64 + ep];
;                             s_ = ((unsigned)(voff + ep) < 16u) ? s_ : -INFINITY;
;                             sc[wl][blk][e] = s_; mx = fmaxf(mx, s_);
;                         }
;                 mx = fmaxf(mx, __shfl_xor(mx, 16)); mx = fmaxf(mx, __shfl_xor(mx, 32));
	v_add_f32_e32 v40, v40, v74
	v_cndmask_b32_e32 v74, v187, v40, vcc
	v_add_f32_e32 v40, v41, v75
	s_waitcnt lgkmcnt(2)
	v_add_f32_e32 v41, v42, v76
	v_cndmask_b32_e64 v75, v187, v40, s[6:7]
	v_cndmask_b32_e64 v76, v187, v41, s[8:9]
	v_add_f32_e32 v41, v43, v77
	s_waitcnt lgkmcnt(1)
	v_add_f32_e32 v36, v36, v78
	v_max3_f32 v40, v88, v74, v75
	v_cndmask_b32_e64 v77, v187, v41, s[10:11]
	v_cndmask_b32_e64 v78, v187, v36, s[12:13]
	v_add_f32_e32 v36, v37, v79
	s_waitcnt lgkmcnt(0)
	v_add_f32_e32 v37, v38, v80
	v_max3_f32 v40, v40, v76, v77
	v_cndmask_b32_e64 v79, v187, v36, s[14:15]
	v_cndmask_b32_e64 v80, v187, v37, s[16:17]
	v_add_f32_e32 v37, v39, v81
	v_max3_f32 v36, v40, v78, v79
	v_cndmask_b32_e64 v81, v187, v37, s[18:19]
	v_max3_f32 v88, v36, v80, v81
	v_add_u32_e32 v36, 0x97c, v218
	ds_read2_b32 v[36:37], v36 offset1:1
	v_add_u32_e32 v38, 0x984, v218
	v_add_u32_e32 v40, 0x98c, v218
	v_add_u32_e32 v42, 0x994, v218
	ds_read2_b32 v[38:39], v38 offset1:1
	ds_read2_b32 v[40:41], v40 offset1:1
	ds_read2_b32 v[42:43], v42 offset1:1
	s_waitcnt lgkmcnt(3)
	v_add_f32_e32 v36, v50, v36
	v_cndmask_b32_e32 v50, v187, v36, vcc
	v_add_f32_e32 v36, v51, v37
	s_waitcnt lgkmcnt(2)
	v_add_f32_e32 v37, v52, v38
	v_cndmask_b32_e64 v52, v187, v37, s[8:9]
	v_add_f32_e32 v37, v53, v39
	v_cndmask_b32_e64 v53, v187, v37, s[10:11]
	s_waitcnt lgkmcnt(1)
	v_add_f32_e32 v37, v44, v40
	v_cndmask_b32_e64 v51, v187, v36, s[6:7]
	v_cndmask_b32_e64 v44, v187, v37, s[12:13]
	v_add_f32_e32 v37, v45, v41
	v_max3_f32 v36, v88, v50, v51
	v_cndmask_b32_e64 v45, v187, v37, s[14:15]
	s_waitcnt lgkmcnt(0)
	v_add_f32_e32 v37, v46, v42
	v_max3_f32 v36, v36, v52, v53
	v_cndmask_b32_e64 v46, v187, v37, s[16:17]
	v_add_f32_e32 v37, v47, v43
	v_max3_f32 v36, v36, v44, v45
	v_cndmask_b32_e64 v47, v187, v37, s[18:19]
	v_max3_f32 v88, v36, v46, v47
	v_add_u32_e32 v36, 0xa7c, v218
	ds_read2_b32 v[36:37], v36 offset1:1
	v_add_u32_e32 v38, 0xa84, v218
	v_add_u32_e32 v40, 0xa8c, v218
	v_add_u32_e32 v42, 0xa94, v218
	ds_read2_b32 v[38:39], v38 offset1:1
	ds_read2_b32 v[40:41], v40 offset1:1
	ds_read2_b32 v[42:43], v42 offset1:1
	s_waitcnt lgkmcnt(3)
	v_add_f32_e32 v36, v54, v36
	v_cndmask_b32_e32 v54, v187, v36, vcc
	v_add_f32_e32 v36, v55, v37
	s_waitcnt lgkmcnt(2)
	v_add_f32_e32 v37, v56, v38
	v_cndmask_b32_e64 v56, v187, v37, s[8:9]
	v_add_f32_e32 v37, v57, v39
	v_cndmask_b32_e64 v57, v187, v37, s[10:11]
	s_waitcnt lgkmcnt(1)
	v_add_f32_e32 v37, v58, v40
	v_cndmask_b32_e64 v55, v187, v36, s[6:7]
	v_cndmask_b32_e64 v58, v187, v37, s[12:13]
	v_add_f32_e32 v37, v59, v41
	v_max3_f32 v36, v88, v54, v55
	v_cndmask_b32_e64 v59, v187, v37, s[14:15]
	s_waitcnt lgkmcnt(0)
	v_add_f32_e32 v37, v60, v42
	v_max3_f32 v36, v36, v56, v57
	v_cndmask_b32_e64 v60, v187, v37, s[16:17]
	v_add_f32_e32 v37, v61, v43
	v_max3_f32 v36, v36, v58, v59
	v_cndmask_b32_e64 v61, v187, v37, s[18:19]
	v_max3_f32 v88, v36, v60, v61
	v_add_u32_e32 v36, 0xb7c, v218
	ds_read2_b32 v[36:37], v36 offset1:1
	v_add_u32_e32 v38, 0xb84, v218
	v_add_u32_e32 v40, 0xb8c, v218
	v_add_u32_e32 v42, 0xb94, v218
	ds_read2_b32 v[38:39], v38 offset1:1
	ds_read2_b32 v[40:41], v40 offset1:1
	ds_read2_b32 v[42:43], v42 offset1:1
	s_waitcnt lgkmcnt(3)
	v_add_f32_e32 v36, v66, v36
	v_cndmask_b32_e32 v66, v187, v36, vcc
	v_add_f32_e32 v36, v67, v37
	s_waitcnt lgkmcnt(2)
	v_add_f32_e32 v37, v68, v38
	v_cndmask_b32_e64 v68, v187, v37, s[8:9]
	v_add_f32_e32 v37, v69, v39
	v_cndmask_b32_e64 v69, v187, v37, s[10:11]
	s_waitcnt lgkmcnt(1)
	v_add_f32_e32 v37, v62, v40
	v_cndmask_b32_e64 v67, v187, v36, s[6:7]
	v_cndmask_b32_e64 v62, v187, v37, s[12:13]
	v_add_f32_e32 v37, v63, v41
	v_max3_f32 v36, v88, v66, v67
	v_cndmask_b32_e64 v63, v187, v37, s[14:15]
	s_waitcnt lgkmcnt(0)
	v_add_f32_e32 v37, v64, v42
	v_max3_f32 v36, v36, v68, v69
	v_cndmask_b32_e64 v64, v187, v37, s[16:17]
	v_add_f32_e32 v37, v65, v43
	v_max3_f32 v36, v36, v62, v63
	v_cndmask_b32_e64 v65, v187, v37, s[18:19]
	v_max3_f32 v88, v36, v64, v65
	v_add_u32_e32 v36, 0xc7c, v218
	ds_read2_b32 v[36:37], v36 offset1:1
	v_add_u32_e32 v38, 0xc84, v218
	v_add_u32_e32 v40, 0xc8c, v218
	v_add_u32_e32 v42, 0xc94, v218
	ds_read2_b32 v[38:39], v38 offset1:1
	ds_read2_b32 v[40:41], v40 offset1:1
	ds_read2_b32 v[42:43], v42 offset1:1
	s_waitcnt lgkmcnt(3)
	v_add_f32_e32 v36, v70, v36
	v_cndmask_b32_e32 v70, v187, v36, vcc
	v_add_f32_e32 v36, v71, v37
	s_waitcnt lgkmcnt(2)
	v_add_f32_e32 v37, v72, v38
	v_cndmask_b32_e64 v71, v187, v36, s[6:7]
	v_cndmask_b32_e64 v72, v187, v37, s[8:9]
	v_add_f32_e32 v37, v73, v39
	s_waitcnt lgkmcnt(1)
	v_add_f32_e32 v32, v32, v40
	v_max3_f32 v36, v88, v70, v71
	v_cndmask_b32_e64 v73, v187, v37, s[10:11]
	v_cndmask_b32_e64 v40, v187, v32, s[12:13]
	v_add_f32_e32 v32, v33, v41
	s_waitcnt lgkmcnt(0)
	v_add_f32_e32 v33, v34, v42
	v_max3_f32 v36, v36, v72, v73
	v_cndmask_b32_e64 v41, v187, v32, s[14:15]
	v_cndmask_b32_e64 v42, v187, v33, s[16:17]
	v_add_f32_e32 v33, v35, v43
	v_max3_f32 v32, v36, v40, v41
	v_cndmask_b32_e64 v43, v187, v33, s[18:19]
	v_max3_f32 v88, v32, v42, v43
	v_add_u32_e32 v32, 0xd7c, v218
	ds_read2_b32 v[32:33], v32 offset1:1
	v_add_u32_e32 v34, 0xd84, v218
	v_add_u32_e32 v36, 0xd8c, v218
	v_add_u32_e32 v38, 0xd94, v218
	ds_read2_b32 v[34:35], v34 offset1:1
	ds_read2_b32 v[36:37], v36 offset1:1
	ds_read2_b32 v[38:39], v38 offset1:1
	s_waitcnt lgkmcnt(3)
	v_add_f32_e32 v28, v28, v32
	v_cndmask_b32_e32 v89, v187, v28, vcc
	v_add_f32_e32 v28, v29, v33
	v_cndmask_b32_e64 v90, v187, v28, s[6:7]
	s_waitcnt lgkmcnt(2)
	v_add_f32_e32 v29, v30, v34
	v_max3_f32 v28, v88, v89, v90
	v_cndmask_b32_e64 v88, v187, v29, s[8:9]
	v_add_f32_e32 v29, v31, v35
	s_waitcnt lgkmcnt(1)
; #define LAS __attribute__((address_space(3)))
; __device__ __forceinline__ unsigned cvt_pk_bf16(float lo, float hi) { unsigned r; asm volatile("v_cvt_pk_bf16_f32 %0, %1, %2" : "=v"(r) : "v"(lo), "v"(hi)); return r; }
; __device__ __forceinline__ void p2_attention(Frame& F, const bf16_t* Qg, const bf16_t* Kg, const bf16_t* Vg, bf16_t* MIX) {
;     ...
;                 const LAS float* tab = (const LAS float*)(lds + AT_TAB) + (rs - r + 7) * 64 + 16 + (kcol0 - cq + 15) + 8 * g;
;                 const int voff = kcol0 + 8 * g - cs;
;                 float mx = -INFINITY;
; #pragma unroll
;                 for (int wl = 0; wl < 8; ++wl)
; #pragma unroll
;                     for (int blk = 0; blk < 2; ++blk)
; #pragma unroll
;                         for (int e = 0; e < 4; ++e) {
;                             const int ep = 4 * blk + e;
;                             float s_ = sc[wl][blk][e] + tab[wl * 64 + ep];
;                             s_ = ((unsigned)(voff + ep) < 16u) ? s_ : -INFINITY;
;                             sc[wl][blk][e] = s_; mx = fmaxf(mx, s_);
;                         }
;                 mx = fmaxf(mx, __shfl_xor(mx, 16)); mx = fmaxf(mx, __shfl_xor(mx, 32));
;                 float l = 0.f;
; #pragma unroll
;                 for (int wl = 0; wl < 8; ++wl) {
;                     float p[8];
; #pragma unroll
;                     for (int blk = 0; blk < 2; ++blk)
; #pragma unroll
;                         for (int e = 0; e < 4; ++e) { p[4 * blk + e] = __builtin_amdgcn_exp2f(sc[wl][blk][e] - mx); l += p[4 * blk + e]; }
;                     pw[jb][wl].x = cvt_pk_bf16(p[0], p[1]); pw[jb][wl].y = cvt_pk_bf16(p[2], p[3]); pw[jb][wl].z = cvt_pk_bf16(p[4], p[5]); pw[jb][wl].w = cvt_pk_bf16(p[6], p[7]);
;                 }
;                 l += __shfl_xor(l, 16); l += __shfl_xor(l, 32);
;                 il[jb] = __builtin_amdgcn_rcpf(l);
;             }
	v_add_f32_e32 v24, v24, v36
	v_cndmask_b32_e64 v91, v187, v29, s[10:11]
	v_cndmask_b32_e64 v92, v187, v24, s[12:13]
	v_add_f32_e32 v24, v25, v37
	s_waitcnt lgkmcnt(0)
	v_add_f32_e32 v25, v26, v38
	v_max3_f32 v28, v28, v88, v91
	v_cndmask_b32_e64 v93, v187, v24, s[14:15]
	v_cndmask_b32_e64 v94, v187, v25, s[16:17]
	v_add_f32_e32 v25, v27, v39
	v_max3_f32 v24, v28, v92, v93
	v_cndmask_b32_e64 v95, v187, v25, s[18:19]
	v_max3_f32 v32, v24, v94, v95
	v_add_u32_e32 v24, 0xe7c, v218
	ds_read2_b32 v[24:25], v24 offset1:1
	v_add_u32_e32 v26, 0xe84, v218
	v_add_u32_e32 v28, 0xe8c, v218
	v_add_u32_e32 v30, 0xe94, v218
	ds_read2_b32 v[26:27], v26 offset1:1
	ds_read2_b32 v[28:29], v28 offset1:1
	ds_read2_b32 v[30:31], v30 offset1:1
	s_waitcnt lgkmcnt(3)
	v_add_f32_e32 v20, v20, v24
	v_cndmask_b32_e32 v191, v187, v20, vcc
	v_add_f32_e32 v20, v21, v25
	s_waitcnt lgkmcnt(2)
	v_add_f32_e32 v21, v22, v26
	v_cndmask_b32_e64 v192, v187, v20, s[6:7]
	v_cndmask_b32_e64 v193, v187, v21, s[8:9]
	v_add_f32_e32 v21, v23, v27
	s_waitcnt lgkmcnt(1)
	v_add_f32_e32 v16, v16, v28
	v_max3_f32 v20, v32, v191, v192
	v_cndmask_b32_e64 v194, v187, v21, s[10:11]
	v_cndmask_b32_e64 v195, v187, v16, s[12:13]
	v_add_f32_e32 v16, v17, v29
	s_waitcnt lgkmcnt(0)
	v_add_f32_e32 v17, v18, v30
	v_max3_f32 v20, v20, v193, v194
	v_cndmask_b32_e64 v196, v187, v16, s[14:15]
	v_cndmask_b32_e64 v197, v187, v17, s[16:17]
	v_add_f32_e32 v17, v19, v31
	v_max3_f32 v16, v20, v195, v196
	v_cndmask_b32_e64 v198, v187, v17, s[18:19]
	v_max3_f32 v16, v16, v197, v198
	ds_bpermute_b32 v17, v186, v16
	s_waitcnt lgkmcnt(0)
	v_max_f32_e32 v17, v17, v17
	v_max_f32_e32 v16, v16, v17
	ds_bpermute_b32 v17, v168, v16
	s_waitcnt lgkmcnt(0)
	v_max_f32_e32 v17, v17, v17
	v_max_f32_e32 v199, v16, v17
	v_sub_f32_e32 v32, v66, v199
	v_exp_f32_e32 v66, v32
	v_sub_f32_e32 v32, v67, v199
	v_exp_f32_e32 v67, v32
	v_sub_f32_e32 v32, v68, v199
	v_exp_f32_e32 v68, v32
	v_sub_f32_e32 v32, v69, v199
	v_exp_f32_e32 v69, v32
	v_sub_f32_e32 v32, v62, v199
	v_exp_f32_e32 v226, v32
	v_sub_f32_e32 v32, v63, v199
	v_exp_f32_e32 v227, v32
	v_sub_f32_e32 v32, v64, v199
	v_exp_f32_e32 v228, v32
	v_sub_f32_e32 v32, v65, v199
	v_sub_f32_e32 v24, v50, v199
	v_exp_f32_e32 v229, v32
	v_sub_f32_e32 v32, v70, v199
	v_exp_f32_e32 v210, v24
	v_sub_f32_e32 v24, v51, v199
	v_exp_f32_e32 v230, v32
	v_sub_f32_e32 v32, v71, v199
	v_exp_f32_e32 v211, v24
	v_sub_f32_e32 v24, v52, v199
	v_exp_f32_e32 v231, v32
	v_sub_f32_e32 v32, v72, v199
	v_exp_f32_e32 v212, v24
	v_sub_f32_e32 v24, v53, v199
	v_exp_f32_e32 v232, v32
	v_sub_f32_e32 v32, v73, v199
	v_sub_f32_e32 v16, v219, v199
	v_sub_f32_e32 v20, v74, v199
	v_exp_f32_e32 v213, v24
	v_sub_f32_e32 v24, v44, v199
	v_sub_f32_e32 v28, v54, v199
	v_exp_f32_e32 v233, v32
	v_sub_f32_e32 v32, v40, v199
	v_sub_f32_e32 v40, v89, v199
	v_sub_f32_e32 v44, v191, v199
	v_exp_f32_e32 v200, v16
	v_sub_f32_e32 v16, v220, v199
	v_exp_f32_e32 v74, v20
	v_sub_f32_e32 v20, v75, v199
	v_exp_f32_e32 v218, v28
	v_sub_f32_e32 v28, v55, v199
	v_exp_f32_e32 v238, v40
	v_sub_f32_e32 v40, v90, v199
	v_exp_f32_e32 v246, v44
	v_sub_f32_e32 v44, v192, v199
	v_exp_f32_e32 v201, v16
	v_sub_f32_e32 v16, v82, v199
	v_exp_f32_e32 v75, v20
	v_sub_f32_e32 v20, v76, v199
	v_exp_f32_e32 v219, v28
	v_sub_f32_e32 v28, v56, v199
	v_exp_f32_e32 v239, v40
	v_sub_f32_e32 v40, v88, v199
	v_exp_f32_e32 v247, v44
	v_sub_f32_e32 v44, v193, v199
	v_exp_f32_e32 v82, v16
	v_sub_f32_e32 v16, v83, v199
	v_exp_f32_e32 v76, v20
	v_sub_f32_e32 v20, v77, v199
	v_exp_f32_e32 v220, v28
	v_sub_f32_e32 v28, v57, v199
	v_exp_f32_e32 v240, v40
	v_sub_f32_e32 v40, v91, v199
	v_exp_f32_e32 v248, v44
	v_sub_f32_e32 v44, v194, v199
	v_exp_f32_e32 v83, v16
	v_sub_f32_e32 v16, v84, v199
	v_exp_f32_e32 v77, v20
	v_sub_f32_e32 v20, v78, v199
	v_exp_f32_e32 v221, v28
	v_sub_f32_e32 v28, v58, v199
	v_exp_f32_e32 v241, v40
	v_sub_f32_e32 v40, v92, v199
	v_exp_f32_e32 v249, v44
	v_sub_f32_e32 v44, v195, v199
	v_exp_f32_e32 v84, v16
	v_sub_f32_e32 v16, v85, v199
	v_exp_f32_e32 v78, v20
	v_sub_f32_e32 v20, v79, v199
	v_exp_f32_e32 v214, v24
	v_sub_f32_e32 v24, v45, v199
	v_exp_f32_e32 v222, v28
	v_sub_f32_e32 v28, v59, v199
	v_exp_f32_e32 v234, v32
	v_sub_f32_e32 v32, v41, v199
	v_exp_f32_e32 v242, v40
	v_sub_f32_e32 v40, v93, v199
	v_exp_f32_e32 v250, v44
	v_sub_f32_e32 v44, v196, v199
	v_exp_f32_e32 v85, v16
	v_sub_f32_e32 v16, v86, v199
	v_exp_f32_e32 v79, v20
	v_sub_f32_e32 v20, v80, v199
	v_exp_f32_e32 v215, v24
	v_sub_f32_e32 v24, v46, v199
	v_exp_f32_e32 v223, v28
	v_sub_f32_e32 v28, v60, v199
	v_exp_f32_e32 v235, v32
	v_sub_f32_e32 v32, v42, v199
	v_exp_f32_e32 v243, v40
	v_sub_f32_e32 v40, v94, v199
	v_exp_f32_e32 v191, v44
	v_sub_f32_e32 v44, v197, v199
	v_exp_f32_e32 v86, v16
	v_sub_f32_e32 v16, v87, v199
	v_exp_f32_e32 v80, v20
	v_sub_f32_e32 v20, v81, v199
	v_exp_f32_e32 v216, v24
	v_sub_f32_e32 v24, v47, v199
	v_exp_f32_e32 v224, v28
	v_sub_f32_e32 v28, v61, v199
	v_exp_f32_e32 v236, v32
	v_sub_f32_e32 v32, v43, v199
	v_exp_f32_e32 v244, v40
	v_sub_f32_e32 v40, v95, v199
	v_exp_f32_e32 v192, v44
	v_sub_f32_e32 v44, v198, v199
	v_exp_f32_e32 v87, v16
	v_cvt_pk_bf16_f32 v16, v200, v201
	v_cvt_pk_bf16_f32 v17, v82, v83
	v_cvt_pk_bf16_f32 v18, v84, v85
	v_cvt_pk_bf16_f32 v19, v86, v87
	v_exp_f32_e32 v81, v20
	v_cvt_pk_bf16_f32 v20, v74, v75
	v_cvt_pk_bf16_f32 v21, v76, v77
	v_cvt_pk_bf16_f32 v22, v78, v79
	v_cvt_pk_bf16_f32 v23, v80, v81
	v_exp_f32_e32 v217, v24
	v_cvt_pk_bf16_f32 v24, v210, v211
	v_cvt_pk_bf16_f32 v25, v212, v213
	v_cvt_pk_bf16_f32 v26, v214, v215
	v_cvt_pk_bf16_f32 v27, v216, v217
	v_exp_f32_e32 v225, v28
	v_cvt_pk_bf16_f32 v28, v218, v219
	v_cvt_pk_bf16_f32 v29, v220, v221
	v_cvt_pk_bf16_f32 v30, v222, v223
	v_cvt_pk_bf16_f32 v31, v224, v225
	v_cvt_pk_bf16_f32 v36, v66, v67
	v_cvt_pk_bf16_f32 v37, v68, v69
	v_cvt_pk_bf16_f32 v38, v226, v227
	v_cvt_pk_bf16_f32 v39, v228, v229
	v_exp_f32_e32 v237, v32
	v_cvt_pk_bf16_f32 v32, v230, v231
	v_cvt_pk_bf16_f32 v33, v232, v233
	v_cvt_pk_bf16_f32 v34, v234, v235
	v_cvt_pk_bf16_f32 v35, v236, v237
	v_exp_f32_e32 v245, v40
	v_cvt_pk_bf16_f32 v40, v238, v239
	v_cvt_pk_bf16_f32 v41, v240, v241
	v_cvt_pk_bf16_f32 v42, v242, v243
	v_cvt_pk_bf16_f32 v43, v244, v245
	v_exp_f32_e32 v193, v44
	v_cvt_pk_bf16_f32 v44, v246, v247
	v_cvt_pk_bf16_f32 v45, v248, v249
	v_cvt_pk_bf16_f32 v46, v250, v191
	v_cvt_pk_bf16_f32 v47, v192, v193
	ds_read_b128 v[50:53], v251 offset:1024
	ds_read_b128 v[54:57], v251 offset:1536
	s_waitcnt lgkmcnt(1)
; #define LAS __attribute__((address_space(3)))
; __device__ __forceinline__ void p2_attention(Frame& F, const bf16_t* Qg, const bf16_t* Kg, const bf16_t* Vg, bf16_t* MIX) {
;     ...
; #pragma unroll
;                     for (int wl = 0; wl < 8; ++wl)
; #pragma unroll
;                         for (int blk = 0; blk < 2; ++blk) {
;                             const bf16x8 k0 = *(const LAS bf16x8*)(k0p + wl * 5120 + blk * 512), k1 = *(const LAS bf16x8*)(k1p + wl * 5120 + blk * 512);
;                             f32x4 a = (f32x4){0.f, 0.f, 0.f, 0.f};
;                             a = __builtin_amdgcn_mfma_f32_16x16x32_bf16(k0, qf[jb][0], a, 0, 0, 0);
;                             a = __builtin_amdgcn_mfma_f32_16x16x32_bf16(k1, qf[jb][1], a, 0, 0, 0);
;                             sc[wl][blk] = a;
;                         }
;                 }
;                 const LAS float* tab = (const LAS float*)(lds + AT_TAB) + (rs - r + 7) * 64 + 16 + (kcol0 - cq + 15) + 8 * g;
;                 const int voff = kcol0 + 8 * g - cs;
;                 float mx = -INFINITY;
; #pragma unroll
;                 for (int wl = 0; wl < 8; ++wl)
; #pragma unroll
;                     for (int blk = 0; blk < 2; ++blk)
; #pragma unroll
;                         for (int e = 0; e < 4; ++e) {
;                             const int ep = 4 * blk + e;
;                             float s_ = sc[wl][blk][e] + tab[wl * 64 + ep];
;                             s_ = ((unsigned)(voff + ep) < 16u) ? s_ : -INFINITY;
;                             sc[wl][blk][e] = s_; mx = fmaxf(mx, s_);
;                         }
;                 mx = fmaxf(mx, __shfl_xor(mx, 16)); mx = fmaxf(mx, __shfl_xor(mx, 32));
;                 float l = 0.f;
; #pragma unroll
;                 for (int wl = 0; wl < 8; ++wl) {
;                     float p[8];
; #pragma unroll
;                     for (int blk = 0; blk < 2; ++blk)
; #pragma unroll
;                         for (int e = 0; e < 4; ++e) { p[4 * blk + e] = __builtin_amdgcn_exp2f(sc[wl][blk][e] - mx); l += p[4 * blk + e]; }
;                     pw[jb][wl].x = cvt_pk_bf16(p[0], p[1]); pw[jb][wl].y = cvt_pk_bf16(p[2], p[3]); pw[jb][wl].z = cvt_pk_bf16(p[4], p[5]); pw[jb][wl].w = cvt_pk_bf16(p[6], p[7]);
;                 }
;                 l += __shfl_xor(l, 16); l += __shfl_xor(l, 32);
	v_mfma_f32_16x16x32_bf16 v[50:53], v[50:53], v[8:11], 0
	ds_read_b128 v[58:61], v49 offset:1024
	ds_read_b128 v[62:65], v49 offset:1536
	s_waitcnt lgkmcnt(1)
	v_mfma_f32_16x16x32_bf16 v[194:197], v[58:61], v[12:15], v[50:53]
	s_nop 3
	v_add_f32_e32 v50, 0, v200
	v_add_f32_e32 v58, v201, v50
	ds_read_b128 v[50:53], v251 offset:6144
	v_add_f32_e32 v58, v82, v58
	v_mfma_f32_16x16x32_bf16 v[54:57], v[54:57], v[8:11], 0
	v_add_f32_e32 v70, v83, v58
	ds_read_b128 v[58:61], v49 offset:6144
	s_waitcnt lgkmcnt(2)
	v_mfma_f32_16x16x32_bf16 v[198:201], v[62:65], v[12:15], v[54:57]
	s_nop 3
	v_add_f32_e32 v54, v84, v70
	v_add_f32_e32 v62, v85, v54
	ds_read_b128 v[54:57], v251 offset:6656
	s_waitcnt lgkmcnt(2)
	v_mfma_f32_16x16x32_bf16 v[50:53], v[50:53], v[8:11], 0
	v_add_f32_e32 v62, v86, v62
	v_add_f32_e32 v70, v87, v62
	ds_read_b128 v[62:65], v49 offset:6656
	s_waitcnt lgkmcnt(2)
	v_mfma_f32_16x16x32_bf16 v[202:205], v[58:61], v[12:15], v[50:53]
	s_waitcnt lgkmcnt(1)
	v_mfma_f32_16x16x32_bf16 v[54:57], v[54:57], v[8:11], 0
	s_nop 0
	v_add_f32_e32 v50, v74, v70
	v_add_f32_e32 v58, v75, v50
	ds_read_b128 v[50:53], v251 offset:11264
	v_add_f32_e32 v58, v76, v58
	v_add_f32_e32 v70, v77, v58
	ds_read_b128 v[58:61], v49 offset:11264
	s_waitcnt lgkmcnt(2)
	v_mfma_f32_16x16x32_bf16 v[206:209], v[62:65], v[12:15], v[54:57]
	s_nop 2
	v_add_f32_e32 v54, v78, v70
	v_add_f32_e32 v62, v79, v54
	ds_read_b128 v[54:57], v251 offset:11776
	s_waitcnt lgkmcnt(2)
	v_mfma_f32_16x16x32_bf16 v[50:53], v[50:53], v[8:11], 0
	v_add_f32_e32 v62, v80, v62
	v_add_f32_e32 v70, v81, v62
	ds_read_b128 v[62:65], v49 offset:11776
	s_waitcnt lgkmcnt(2)
	v_mfma_f32_16x16x32_bf16 v[88:91], v[58:61], v[12:15], v[50:53]
	s_waitcnt lgkmcnt(1)
	v_mfma_f32_16x16x32_bf16 v[54:57], v[54:57], v[8:11], 0
	s_nop 0
	v_add_f32_e32 v50, v210, v70
	v_add_f32_e32 v58, v211, v50
	ds_read_b128 v[50:53], v251 offset:16384
	v_add_f32_e32 v58, v212, v58
	v_add_f32_e32 v70, v213, v58
	ds_read_b128 v[58:61], v49 offset:16384
	s_waitcnt lgkmcnt(2)
	v_mfma_f32_16x16x32_bf16 v[92:95], v[62:65], v[12:15], v[54:57]
	ds_read_b128 v[210:213], v251 offset:32256
	s_nop 1
	v_add_f32_e32 v54, v214, v70
	v_add_f32_e32 v62, v215, v54
	ds_read_b128 v[54:57], v251 offset:16896
	s_waitcnt lgkmcnt(3)
	v_mfma_f32_16x16x32_bf16 v[50:53], v[50:53], v[8:11], 0
	v_add_f32_e32 v62, v216, v62
	v_add_f32_e32 v70, v217, v62
	ds_read_b128 v[62:65], v49 offset:16896
	s_waitcnt lgkmcnt(3)
	v_mfma_f32_16x16x32_bf16 v[80:83], v[58:61], v[12:15], v[50:53]
	ds_read_b128 v[214:217], v49 offset:32256
	s_nop 1
	v_add_f32_e32 v50, v218, v70
	v_add_f32_e32 v58, v219, v50
	ds_read_b128 v[50:53], v251 offset:21504
	v_add_f32_e32 v58, v220, v58
	s_waitcnt lgkmcnt(3)
	v_mfma_f32_16x16x32_bf16 v[54:57], v[54:57], v[8:11], 0
	v_add_f32_e32 v70, v221, v58
	ds_read_b128 v[58:61], v49 offset:21504
	ds_read_b128 v[218:221], v49 offset:37376
	s_waitcnt lgkmcnt(4)
	v_mfma_f32_16x16x32_bf16 v[84:87], v[62:65], v[12:15], v[54:57]
	s_nop 2
	v_add_f32_e32 v54, v222, v70
	v_add_f32_e32 v62, v223, v54
	ds_read_b128 v[54:57], v251 offset:22016
	s_waitcnt lgkmcnt(3)
	v_mfma_f32_16x16x32_bf16 v[50:53], v[50:53], v[8:11], 0
	v_add_f32_e32 v62, v224, v62
	v_add_f32_e32 v70, v225, v62
	ds_read_b128 v[62:65], v49 offset:22016
	s_waitcnt lgkmcnt(3)
	v_mfma_f32_16x16x32_bf16 v[72:75], v[58:61], v[12:15], v[50:53]
	s_waitcnt lgkmcnt(1)
	v_mfma_f32_16x16x32_bf16 v[54:57], v[54:57], v[8:11], 0
	s_nop 0
	v_add_f32_e32 v50, v66, v70
	v_add_f32_e32 v58, v67, v50
	ds_read_b128 v[50:53], v251 offset:26624
	v_add_f32_e32 v58, v68, v58
	v_add_f32_e32 v66, v69, v58
	ds_read_b128 v[58:61], v49 offset:26624
	ds_read_b128 v[68:71], v49 offset:27136
	s_waitcnt lgkmcnt(3)
	v_mfma_f32_16x16x32_bf16 v[76:79], v[62:65], v[12:15], v[54:57]
	s_nop 2
	v_add_f32_e32 v54, v226, v66
	v_add_f32_e32 v62, v227, v54
	ds_read_b128 v[54:57], v251 offset:27136
	s_waitcnt lgkmcnt(3)
	v_mfma_f32_16x16x32_bf16 v[50:53], v[50:53], v[8:11], 0
	v_add_f32_e32 v62, v228, v62
	v_add_f32_e32 v62, v229, v62
	s_waitcnt lgkmcnt(2)
	v_mfma_f32_16x16x32_bf16 v[64:67], v[58:61], v[12:15], v[50:53]
	s_waitcnt lgkmcnt(0)
	v_mfma_f32_16x16x32_bf16 v[54:57], v[54:57], v[8:11], 0
	s_nop 1
	v_add_f32_e32 v50, v230, v62
	v_add_f32_e32 v58, v231, v50
	ds_read_b128 v[50:53], v251 offset:31744
	v_add_f32_e32 v58, v232, v58
	v_add_f32_e32 v62, v233, v58
	ds_read_b128 v[58:61], v49 offset:31744
	v_mfma_f32_16x16x32_bf16 v[68:71], v[68:71], v[12:15], v[54:57]
	s_nop 2
	v_add_f32_e32 v54, v234, v62
	s_waitcnt lgkmcnt(1)
	v_mfma_f32_16x16x32_bf16 v[50:53], v[50:53], v[8:11], 0
	v_add_f32_e32 v54, v235, v54
	v_add_f32_e32 v54, v236, v54
	v_add_f32_e32 v54, v237, v54
	s_waitcnt lgkmcnt(0)
	v_mfma_f32_16x16x32_bf16 v[56:59], v[58:61], v[12:15], v[50:53]
	v_mfma_f32_16x16x32_bf16 v[60:63], v[210:213], v[8:11], 0
	s_nop 1
	v_add_f32_e32 v50, v238, v54
	v_add_f32_e32 v54, v239, v50
	ds_read_b128 v[50:53], v251 offset:36864
	ds_read_b128 v[210:213], v49 offset:36864
	v_mfma_f32_16x16x32_bf16 v[60:63], v[214:217], v[12:15], v[60:63]
	ds_read_b128 v[214:217], v251 offset:37376
	v_add_f32_e32 v54, v240, v54
	v_add_f32_e32 v54, v241, v54
	v_add_f32_e32 v54, v242, v54
	s_waitcnt lgkmcnt(2)
	v_mfma_f32_16x16x32_bf16 v[50:53], v[50:53], v[8:11], 0
	v_add_f32_e32 v54, v243, v54
	v_add_f32_e32 v54, v244, v54
	v_add_f32_e32 v222, v245, v54
	s_waitcnt lgkmcnt(1)
	v_mfma_f32_16x16x32_bf16 v[52:55], v[210:213], v[12:15], v[50:53]
	v_add_f32_e32 v49, v246, v222
	v_add_f32_e32 v49, v247, v49
	v_add_f32_e32 v49, v248, v49
	s_waitcnt lgkmcnt(0)
; #define LAS __attribute__((address_space(3)))
; __device__ __forceinline__ void p2_attention(Frame& F, const bf16_t* Qg, const bf16_t* Kg, const bf16_t* Vg, bf16_t* MIX) {
;     ...
; #pragma unroll
;                     for (int wl = 0; wl < 8; ++wl)
; #pragma unroll
;                         for (int blk = 0; blk < 2; ++blk) {
;                             const bf16x8 k0 = *(const LAS bf16x8*)(k0p + wl * 5120 + blk * 512), k1 = *(const LAS bf16x8*)(k1p + wl * 5120 + blk * 512);
;                             f32x4 a = (f32x4){0.f, 0.f, 0.f, 0.f};
;                             a = __builtin_amdgcn_mfma_f32_16x16x32_bf16(k0, qf[jb][0], a, 0, 0, 0);
;                             a = __builtin_amdgcn_mfma_f32_16x16x32_bf16(k1, qf[jb][1], a, 0, 0, 0);
;                             sc[wl][blk] = a;
;                         }
;                 }
;                 const LAS float* tab = (const LAS float*)(lds + AT_TAB) + (rs - r + 7) * 64 + 16 + (kcol0 - cq + 15) + 8 * g;
;                 const int voff = kcol0 + 8 * g - cs;
;                 float mx = -INFINITY;
; #pragma unroll
;                 for (int wl = 0; wl < 8; ++wl)
; #pragma unroll
;                     for (int blk = 0; blk < 2; ++blk)
; #pragma unroll
;                         for (int e = 0; e < 4; ++e) {
;                             const int ep = 4 * blk + e;
;                             float s_ = sc[wl][blk][e] + tab[wl * 64 + ep];
;                             s_ = ((unsigned)(voff + ep) < 16u) ? s_ : -INFINITY;
;                             sc[wl][blk][e] = s_; mx = fmaxf(mx, s_);
;                         }
;                 mx = fmaxf(mx, __shfl_xor(mx, 16)); mx = fmaxf(mx, __shfl_xor(mx, 32));
	v_mfma_f32_16x16x32_bf16 v[210:213], v[214:217], v[8:11], 0
	v_add_f32_e32 v49, v249, v49
	v_or_b32_e32 v214, 16, v48
	v_add_f32_e32 v222, v250, v49
	v_mfma_f32_16x16x32_bf16 v[48:51], v[218:221], v[12:15], v[210:213]
	s_nop 3
	v_sub_u32_e32 v211, s0, v214
	v_lshl_add_u32 v189, v211, 2, v189
	v_min_u32_e32 v210, 56, v214
	v_add_u32_e32 v211, 0x79c, v189
	v_sub_u32_e32 v190, v190, v210
	ds_read2_b32 v[210:211], v211 offset1:1
	v_add_u32_e32 v212, 0x7a4, v189
	v_add_u32_e32 v214, 0x7ac, v189
	v_add_u32_e32 v216, 0x7b4, v189
	v_add_u32_e32 v218, 8, v190
	ds_read2_b32 v[212:213], v212 offset1:1
	ds_read2_b32 v[214:215], v214 offset1:1
	ds_read2_b32 v[216:217], v216 offset1:1
	s_waitcnt lgkmcnt(3)
	v_add_f32_e32 v194, v194, v210
	v_cmp_gt_u32_e32 vcc, 16, v218
	s_nop 1
	v_cndmask_b32_e32 v210, v187, v194, vcc
	v_add_f32_e32 v194, v195, v211
	v_add_u32_e32 v195, 9, v190
	v_cmp_gt_u32_e64 s[6:7], 16, v195
	s_waitcnt lgkmcnt(2)
	v_add_f32_e32 v195, v196, v212
	v_add_u32_e32 v196, 10, v190
	v_cmp_gt_u32_e64 s[8:9], 16, v196
	v_add_u32_e32 v196, 11, v190
	v_cmp_gt_u32_e64 s[10:11], 16, v196
	v_cndmask_b32_e64 v212, v187, v195, s[8:9]
	v_add_f32_e32 v195, v197, v213
	v_add_u32_e32 v196, 12, v190
	v_cndmask_b32_e64 v213, v187, v195, s[10:11]
	s_waitcnt lgkmcnt(1)
	v_add_f32_e32 v195, v198, v214
	v_cmp_gt_u32_e64 s[12:13], 16, v196
	v_add_u32_e32 v196, 13, v190
	v_cndmask_b32_e64 v211, v187, v194, s[6:7]
	v_cndmask_b32_e64 v214, v187, v195, s[12:13]
	v_add_f32_e32 v195, v199, v215
	v_cmp_gt_u32_e64 s[14:15], 16, v196
	v_add_u32_e32 v196, 14, v190
	v_max3_f32 v194, v210, s88, v211
	v_cndmask_b32_e64 v215, v187, v195, s[14:15]
	s_waitcnt lgkmcnt(0)
	v_add_f32_e32 v195, v200, v216
	v_cmp_gt_u32_e64 s[16:17], 16, v196
	v_add_u32_e32 v190, 15, v190
	v_max3_f32 v194, v194, v212, v213
	v_cndmask_b32_e64 v216, v187, v195, s[16:17]
	v_add_f32_e32 v195, v201, v217
	v_cmp_gt_u32_e64 s[18:19], 16, v190
	v_max3_f32 v194, v194, v214, v215
	v_add_u32_e32 v196, 0x8a4, v189
	v_cndmask_b32_e64 v190, v187, v195, s[18:19]
	v_max3_f32 v217, v194, v216, v190
	v_add_u32_e32 v194, 0x89c, v189
	ds_read2_b32 v[194:195], v194 offset1:1
	v_add_u32_e32 v198, 0x8ac, v189
	v_add_u32_e32 v200, 0x8b4, v189
	ds_read2_b32 v[196:197], v196 offset1:1
	ds_read2_b32 v[198:199], v198 offset1:1
	ds_read2_b32 v[200:201], v200 offset1:1
	s_waitcnt lgkmcnt(3)
	v_add_f32_e32 v194, v202, v194
	v_cndmask_b32_e32 v202, v187, v194, vcc
	v_add_f32_e32 v194, v203, v195
	s_waitcnt lgkmcnt(2)
	v_add_f32_e32 v195, v204, v196
	v_cndmask_b32_e64 v204, v187, v195, s[8:9]
	v_add_f32_e32 v195, v205, v197
	v_cndmask_b32_e64 v205, v187, v195, s[10:11]
	s_waitcnt lgkmcnt(1)
	v_add_f32_e32 v195, v206, v198
	v_cndmask_b32_e64 v203, v187, v194, s[6:7]
	v_cndmask_b32_e64 v206, v187, v195, s[12:13]
	v_add_f32_e32 v195, v207, v199
	v_max3_f32 v194, v217, v202, v203
	v_cndmask_b32_e64 v207, v187, v195, s[14:15]
	s_waitcnt lgkmcnt(0)
	v_add_f32_e32 v195, v208, v200
	v_max3_f32 v194, v194, v204, v205
	v_cndmask_b32_e64 v208, v187, v195, s[16:17]
	v_add_f32_e32 v195, v209, v201
	v_max3_f32 v194, v194, v206, v207
	v_cndmask_b32_e64 v209, v187, v195, s[18:19]
	v_max3_f32 v217, v194, v208, v209
	v_add_u32_e32 v194, 0x99c, v189
	ds_read2_b32 v[194:195], v194 offset1:1
	v_add_u32_e32 v196, 0x9a4, v189
	v_add_u32_e32 v198, 0x9ac, v189
	v_add_u32_e32 v200, 0x9b4, v189
	ds_read2_b32 v[196:197], v196 offset1:1
	ds_read2_b32 v[198:199], v198 offset1:1
	ds_read2_b32 v[200:201], v200 offset1:1
	s_waitcnt lgkmcnt(3)
	v_add_f32_e32 v88, v88, v194
	v_cndmask_b32_e32 v194, v187, v88, vcc
	v_add_f32_e32 v88, v89, v195
	s_waitcnt lgkmcnt(2)
	v_add_f32_e32 v89, v90, v196
	v_cndmask_b32_e64 v196, v187, v89, s[8:9]
	v_add_f32_e32 v89, v91, v197
	v_cndmask_b32_e64 v197, v187, v89, s[10:11]
	s_waitcnt lgkmcnt(1)
	v_add_f32_e32 v89, v92, v198
	v_cndmask_b32_e64 v195, v187, v88, s[6:7]
	v_cndmask_b32_e64 v198, v187, v89, s[12:13]
	v_add_f32_e32 v89, v93, v199
	v_max3_f32 v88, v217, v194, v195
	v_cndmask_b32_e64 v199, v187, v89, s[14:15]
	s_waitcnt lgkmcnt(0)
	v_add_f32_e32 v89, v94, v200
	v_max3_f32 v88, v88, v196, v197
	v_cndmask_b32_e64 v200, v187, v89, s[16:17]
	v_add_f32_e32 v89, v95, v201
	v_max3_f32 v88, v88, v198, v199
	v_cndmask_b32_e64 v201, v187, v89, s[18:19]
	v_max3_f32 v217, v88, v200, v201
	v_add_u32_e32 v88, 0xa9c, v189
	ds_read2_b32 v[88:89], v88 offset1:1
	v_add_u32_e32 v90, 0xaa4, v189
	v_add_u32_e32 v92, 0xaac, v189
	v_add_u32_e32 v94, 0xab4, v189
	ds_read2_b32 v[90:91], v90 offset1:1
	ds_read2_b32 v[92:93], v92 offset1:1
	ds_read2_b32 v[94:95], v94 offset1:1
	s_waitcnt lgkmcnt(3)
	v_add_f32_e32 v80, v80, v88
	v_cndmask_b32_e32 v88, v187, v80, vcc
	v_add_f32_e32 v80, v81, v89
	s_waitcnt lgkmcnt(2)
	v_add_f32_e32 v81, v82, v90
	v_cndmask_b32_e64 v90, v187, v81, s[8:9]
	v_add_f32_e32 v81, v83, v91
	v_cndmask_b32_e64 v91, v187, v81, s[10:11]
	s_waitcnt lgkmcnt(1)
	v_add_f32_e32 v81, v84, v92
	v_cndmask_b32_e64 v89, v187, v80, s[6:7]
	v_cndmask_b32_e64 v92, v187, v81, s[12:13]
	v_add_f32_e32 v81, v85, v93
	v_max3_f32 v80, v217, v88, v89
	v_cndmask_b32_e64 v93, v187, v81, s[14:15]
	s_waitcnt lgkmcnt(0)
	v_add_f32_e32 v81, v86, v94
	v_max3_f32 v80, v80, v90, v91
	v_cndmask_b32_e64 v94, v187, v81, s[16:17]
	v_add_f32_e32 v81, v87, v95
	v_max3_f32 v80, v80, v92, v93
	v_cndmask_b32_e64 v95, v187, v81, s[18:19]
	v_max3_f32 v217, v80, v94, v95
	v_add_u32_e32 v80, 0xb9c, v189
	ds_read2_b32 v[80:81], v80 offset1:1
	v_add_u32_e32 v82, 0xba4, v189
	v_add_u32_e32 v84, 0xbac, v189
	v_add_u32_e32 v86, 0xbb4, v189
	ds_read2_b32 v[82:83], v82 offset1:1
	ds_read2_b32 v[84:85], v84 offset1:1
	ds_read2_b32 v[86:87], v86 offset1:1
	s_waitcnt lgkmcnt(3)
; #define LAS __attribute__((address_space(3)))
; __device__ __forceinline__ unsigned cvt_pk_bf16(float lo, float hi) { unsigned r; asm volatile("v_cvt_pk_bf16_f32 %0, %1, %2" : "=v"(r) : "v"(lo), "v"(hi)); return r; }
; __device__ __forceinline__ void p2_attention(Frame& F, const bf16_t* Qg, const bf16_t* Kg, const bf16_t* Vg, bf16_t* MIX) {
;     ...
;                 const LAS float* tab = (const LAS float*)(lds + AT_TAB) + (rs - r + 7) * 64 + 16 + (kcol0 - cq + 15) + 8 * g;
;                 const int voff = kcol0 + 8 * g - cs;
;                 float mx = -INFINITY;
; #pragma unroll
;                 for (int wl = 0; wl < 8; ++wl)
; #pragma unroll
;                     for (int blk = 0; blk < 2; ++blk)
; #pragma unroll
;                         for (int e = 0; e < 4; ++e) {
;                             const int ep = 4 * blk + e;
;                             float s_ = sc[wl][blk][e] + tab[wl * 64 + ep];
;                             s_ = ((unsigned)(voff + ep) < 16u) ? s_ : -INFINITY;
;                             sc[wl][blk][e] = s_; mx = fmaxf(mx, s_);
;                         }
;                 mx = fmaxf(mx, __shfl_xor(mx, 16)); mx = fmaxf(mx, __shfl_xor(mx, 32));
;                 float l = 0.f;
; #pragma unroll
;                 for (int wl = 0; wl < 8; ++wl) {
;                     float p[8];
; #pragma unroll
;                     for (int blk = 0; blk < 2; ++blk)
; #pragma unroll
;                         for (int e = 0; e < 4; ++e) { p[4 * blk + e] = __builtin_amdgcn_exp2f(sc[wl][blk][e] - mx); l += p[4 * blk + e]; }
;                     pw[jb][wl].x = cvt_pk_bf16(p[0], p[1]); pw[jb][wl].y = cvt_pk_bf16(p[2], p[3]); pw[jb][wl].z = cvt_pk_bf16(p[4], p[5]); pw[jb][wl].w = cvt_pk_bf16(p[6], p[7]);
;                 }
;                 l += __shfl_xor(l, 16); l += __shfl_xor(l, 32);
;                 il[jb] = __builtin_amdgcn_rcpf(l);
	v_add_f32_e32 v72, v72, v80
	v_cndmask_b32_e32 v80, v187, v72, vcc
	v_add_f32_e32 v72, v73, v81
	v_cndmask_b32_e64 v81, v187, v72, s[6:7]
	s_waitcnt lgkmcnt(2)
	v_add_f32_e32 v73, v74, v82
	v_max3_f32 v72, v217, v80, v81
	v_cndmask_b32_e64 v217, v187, v73, s[8:9]
	v_add_f32_e32 v73, v75, v83
	v_cndmask_b32_e64 v218, v187, v73, s[10:11]
	s_waitcnt lgkmcnt(1)
	v_add_f32_e32 v73, v76, v84
	v_cndmask_b32_e64 v84, v187, v73, s[12:13]
	v_add_f32_e32 v73, v77, v85
	v_cndmask_b32_e64 v85, v187, v73, s[14:15]
	s_waitcnt lgkmcnt(0)
	v_add_f32_e32 v73, v78, v86
	v_max3_f32 v72, v72, v217, v218
	v_cndmask_b32_e64 v86, v187, v73, s[16:17]
	v_add_f32_e32 v73, v79, v87
	v_max3_f32 v72, v72, v84, v85
	v_cndmask_b32_e64 v87, v187, v73, s[18:19]
	v_max3_f32 v82, v72, v86, v87
	v_add_u32_e32 v72, 0xc9c, v189
	ds_read2_b32 v[72:73], v72 offset1:1
	v_add_u32_e32 v74, 0xca4, v189
	v_add_u32_e32 v76, 0xcac, v189
	v_add_u32_e32 v78, 0xcb4, v189
	ds_read2_b32 v[74:75], v74 offset1:1
	ds_read2_b32 v[76:77], v76 offset1:1
	ds_read2_b32 v[78:79], v78 offset1:1
	s_waitcnt lgkmcnt(3)
	v_add_f32_e32 v64, v64, v72
	v_cndmask_b32_e32 v72, v187, v64, vcc
	v_add_f32_e32 v64, v65, v73
	s_waitcnt lgkmcnt(2)
	v_add_f32_e32 v65, v66, v74
	v_cndmask_b32_e64 v74, v187, v65, s[8:9]
	v_add_f32_e32 v65, v67, v75
	v_cndmask_b32_e64 v75, v187, v65, s[10:11]
	s_waitcnt lgkmcnt(1)
	v_add_f32_e32 v65, v68, v76
	v_cndmask_b32_e64 v73, v187, v64, s[6:7]
	v_cndmask_b32_e64 v76, v187, v65, s[12:13]
	v_add_f32_e32 v65, v69, v77
	v_max3_f32 v64, v82, v72, v73
	v_cndmask_b32_e64 v77, v187, v65, s[14:15]
	s_waitcnt lgkmcnt(0)
	v_add_f32_e32 v65, v70, v78
	v_max3_f32 v64, v64, v74, v75
	v_cndmask_b32_e64 v78, v187, v65, s[16:17]
	v_add_f32_e32 v65, v71, v79
	v_max3_f32 v64, v64, v76, v77
	v_cndmask_b32_e64 v79, v187, v65, s[18:19]
	v_max3_f32 v82, v64, v78, v79
	v_add_u32_e32 v64, 0xd9c, v189
	ds_read2_b32 v[64:65], v64 offset1:1
	v_add_u32_e32 v66, 0xda4, v189
	v_add_u32_e32 v68, 0xdac, v189
	v_add_u32_e32 v70, 0xdb4, v189
	ds_read2_b32 v[66:67], v66 offset1:1
	ds_read2_b32 v[68:69], v68 offset1:1
	ds_read2_b32 v[70:71], v70 offset1:1
	s_waitcnt lgkmcnt(3)
	v_add_f32_e32 v56, v56, v64
	v_cndmask_b32_e32 v219, v187, v56, vcc
	v_add_f32_e32 v56, v57, v65
	s_waitcnt lgkmcnt(2)
	v_add_f32_e32 v57, v58, v66
	v_cndmask_b32_e64 v221, v187, v57, s[8:9]
	v_add_f32_e32 v57, v59, v67
	v_cndmask_b32_e64 v223, v187, v57, s[10:11]
	s_waitcnt lgkmcnt(1)
	v_add_f32_e32 v57, v60, v68
	v_cndmask_b32_e64 v220, v187, v56, s[6:7]
	v_cndmask_b32_e64 v224, v187, v57, s[12:13]
	v_add_f32_e32 v57, v61, v69
	v_max3_f32 v56, v82, v219, v220
	v_cndmask_b32_e64 v225, v187, v57, s[14:15]
	s_waitcnt lgkmcnt(0)
	v_add_f32_e32 v57, v62, v70
	v_max3_f32 v56, v56, v221, v223
	v_cndmask_b32_e64 v226, v187, v57, s[16:17]
	v_add_f32_e32 v57, v63, v71
	v_max3_f32 v56, v56, v224, v225
	v_cndmask_b32_e64 v227, v187, v57, s[18:19]
	v_max3_f32 v64, v56, v226, v227
	v_add_u32_e32 v56, 0xe9c, v189
	ds_read2_b32 v[56:57], v56 offset1:1
	v_add_u32_e32 v58, 0xea4, v189
	v_add_u32_e32 v60, 0xeac, v189
	v_add_u32_e32 v62, 0xeb4, v189
	ds_read2_b32 v[58:59], v58 offset1:1
	ds_read2_b32 v[60:61], v60 offset1:1
	ds_read2_b32 v[62:63], v62 offset1:1
	s_waitcnt lgkmcnt(3)
	v_add_f32_e32 v52, v52, v56
	v_cndmask_b32_e32 v189, v187, v52, vcc
	v_add_f32_e32 v52, v53, v57
	s_waitcnt lgkmcnt(2)
	v_add_f32_e32 v53, v54, v58
	v_cndmask_b32_e64 v228, v187, v52, s[6:7]
	v_cndmask_b32_e64 v229, v187, v53, s[8:9]
	v_add_f32_e32 v53, v55, v59
	s_waitcnt lgkmcnt(1)
	v_add_f32_e32 v48, v48, v60
	v_max3_f32 v52, v64, v189, v228
	v_cndmask_b32_e64 v230, v187, v53, s[10:11]
	v_cndmask_b32_e64 v231, v187, v48, s[12:13]
	v_add_f32_e32 v48, v49, v61
	s_waitcnt lgkmcnt(0)
	v_add_f32_e32 v49, v50, v62
	v_max3_f32 v52, v52, v229, v230
	v_cndmask_b32_e64 v232, v187, v48, s[14:15]
	v_cndmask_b32_e64 v233, v187, v49, s[16:17]
	v_add_f32_e32 v49, v51, v63
	v_max3_f32 v48, v52, v231, v232
	v_cndmask_b32_e64 v234, v187, v49, s[18:19]
	v_max3_f32 v48, v48, v233, v234
	ds_bpermute_b32 v49, v186, v48
	v_add_f32_e32 v50, v191, v222
	v_add_f32_e32 v50, v192, v50
	v_add_f32_e32 v50, v193, v50
	ds_bpermute_b32 v51, v186, v50
	s_waitcnt lgkmcnt(1)
	v_max_f32_e32 v49, v49, v49
	v_max_f32_e32 v48, v48, v49
	ds_bpermute_b32 v49, v168, v48
	s_waitcnt lgkmcnt(1)
	v_add_f32_e32 v82, v50, v51
	ds_bpermute_b32 v83, v168, v82
	s_waitcnt lgkmcnt(1)
; __device__ __forceinline__ unsigned cvt_pk_bf16(float lo, float hi) { unsigned r; asm volatile("v_cvt_pk_bf16_f32 %0, %1, %2" : "=v"(r) : "v"(lo), "v"(hi)); return r; }
; #define ATT_WAIT_BAR() do { asm volatile("s_waitcnt vmcnt(0) lgkmcnt(0)" ::: "memory"); __builtin_amdgcn_s_barrier(); asm volatile("" ::: "memory"); } while (0)
; __device__ __forceinline__ void p2_attention(Frame& F, const bf16_t* Qg, const bf16_t* Kg, const bf16_t* Vg, bf16_t* MIX) {
;     ...
;                 float l = 0.f;
; #pragma unroll
;                 for (int wl = 0; wl < 8; ++wl) {
;                     float p[8];
; #pragma unroll
;                     for (int blk = 0; blk < 2; ++blk)
; #pragma unroll
;                         for (int e = 0; e < 4; ++e) { p[4 * blk + e] = __builtin_amdgcn_exp2f(sc[wl][blk][e] - mx); l += p[4 * blk + e]; }
;                     pw[jb][wl].x = cvt_pk_bf16(p[0], p[1]); pw[jb][wl].y = cvt_pk_bf16(p[2], p[3]); pw[jb][wl].z = cvt_pk_bf16(p[4], p[5]); pw[jb][wl].w = cvt_pk_bf16(p[6], p[7]);
;                 }
;                 l += __shfl_xor(l, 16); l += __shfl_xor(l, 32);
;                 il[jb] = __builtin_amdgcn_rcpf(l);
;             }
;             ATT_WAIT_BAR();
	v_max_f32_e32 v49, v49, v49
	v_max_f32_e32 v191, v48, v49
	v_sub_f32_e32 v48, v210, v191
	v_exp_f32_e32 v48, v48
	v_sub_f32_e32 v49, v211, v191
	v_exp_f32_e32 v49, v49
	v_sub_f32_e32 v50, v212, v191
	v_exp_f32_e32 v50, v50
	v_sub_f32_e32 v51, v213, v191
	v_exp_f32_e32 v51, v51
	v_sub_f32_e32 v53, v214, v191
	v_add_f32_e32 v52, 0, v48
	v_exp_f32_e32 v53, v53
	v_sub_f32_e32 v54, v215, v191
	v_add_f32_e32 v52, v49, v52
	v_exp_f32_e32 v54, v54
	v_sub_f32_e32 v55, v216, v191
	v_add_f32_e32 v52, v50, v52
	v_exp_f32_e32 v55, v55
	v_sub_f32_e32 v56, v190, v191
	v_add_f32_e32 v52, v51, v52
	v_exp_f32_e32 v56, v56
	v_add_f32_e32 v52, v53, v52
	v_cvt_pk_bf16_f32 v48, v48, v49
	v_cvt_pk_bf16_f32 v49, v50, v51
	v_cvt_pk_bf16_f32 v50, v53, v54
	v_sub_f32_e32 v53, v202, v191
	v_add_f32_e32 v52, v54, v52
	v_exp_f32_e32 v53, v53
	v_sub_f32_e32 v54, v203, v191
	v_add_f32_e32 v52, v55, v52
	v_cvt_pk_bf16_f32 v51, v55, v56
	v_exp_f32_e32 v54, v54
	v_sub_f32_e32 v55, v204, v191
	v_add_f32_e32 v52, v56, v52
	v_exp_f32_e32 v55, v55
	v_sub_f32_e32 v56, v205, v191
	v_exp_f32_e32 v56, v56
	v_sub_f32_e32 v57, v206, v191
	v_add_f32_e32 v52, v53, v52
	v_exp_f32_e32 v57, v57
	v_sub_f32_e32 v58, v207, v191
	v_add_f32_e32 v52, v54, v52
	v_exp_f32_e32 v58, v58
	v_sub_f32_e32 v59, v208, v191
	v_add_f32_e32 v52, v55, v52
	v_exp_f32_e32 v59, v59
	v_sub_f32_e32 v60, v209, v191
	v_add_f32_e32 v52, v56, v52
	v_exp_f32_e32 v60, v60
	v_add_f32_e32 v52, v57, v52
	v_add_f32_e32 v52, v58, v52
	v_add_f32_e32 v52, v59, v52
	v_add_f32_e32 v61, v60, v52
	v_cvt_pk_bf16_f32 v52, v53, v54
	v_cvt_pk_bf16_f32 v53, v55, v56
	v_sub_f32_e32 v56, v194, v191
	v_exp_f32_e32 v56, v56
	v_cvt_pk_bf16_f32 v54, v57, v58
	v_sub_f32_e32 v57, v195, v191
	v_exp_f32_e32 v57, v57
	v_sub_f32_e32 v58, v196, v191
	v_cvt_pk_bf16_f32 v55, v59, v60
	v_exp_f32_e32 v58, v58
	v_sub_f32_e32 v59, v197, v191
	v_exp_f32_e32 v59, v59
	v_add_f32_e32 v60, v56, v61
	v_sub_f32_e32 v61, v198, v191
	v_exp_f32_e32 v61, v61
	v_sub_f32_e32 v62, v199, v191
	v_add_f32_e32 v60, v57, v60
	v_exp_f32_e32 v62, v62
	v_sub_f32_e32 v63, v200, v191
	v_add_f32_e32 v60, v58, v60
	v_exp_f32_e32 v63, v63
	v_sub_f32_e32 v64, v201, v191
	v_add_f32_e32 v60, v59, v60
	v_exp_f32_e32 v64, v64
	v_add_f32_e32 v60, v61, v60
	v_cvt_pk_bf16_f32 v56, v56, v57
	v_cvt_pk_bf16_f32 v57, v58, v59
	v_cvt_pk_bf16_f32 v58, v61, v62
	v_sub_f32_e32 v61, v88, v191
	v_add_f32_e32 v60, v62, v60
	v_exp_f32_e32 v61, v61
	v_sub_f32_e32 v62, v89, v191
	v_add_f32_e32 v60, v63, v60
	v_cvt_pk_bf16_f32 v59, v63, v64
	v_exp_f32_e32 v62, v62
	v_sub_f32_e32 v63, v90, v191
	v_add_f32_e32 v60, v64, v60
	v_exp_f32_e32 v63, v63
	v_sub_f32_e32 v64, v91, v191
	v_exp_f32_e32 v64, v64
	v_sub_f32_e32 v65, v92, v191
	v_add_f32_e32 v60, v61, v60
	v_exp_f32_e32 v65, v65
	v_sub_f32_e32 v66, v93, v191
	v_add_f32_e32 v60, v62, v60
	v_exp_f32_e32 v66, v66
	v_sub_f32_e32 v67, v94, v191
	v_add_f32_e32 v60, v63, v60
	v_exp_f32_e32 v67, v67
	v_sub_f32_e32 v68, v95, v191
	v_add_f32_e32 v60, v64, v60
	v_exp_f32_e32 v68, v68
	v_add_f32_e32 v60, v65, v60
	v_add_f32_e32 v60, v66, v60
	v_add_f32_e32 v60, v67, v60
	v_add_f32_e32 v69, v68, v60
	v_cvt_pk_bf16_f32 v60, v61, v62
	v_cvt_pk_bf16_f32 v61, v63, v64
	v_sub_f32_e32 v64, v80, v191
	v_exp_f32_e32 v64, v64
	v_cvt_pk_bf16_f32 v62, v65, v66
	v_sub_f32_e32 v65, v81, v191
	v_exp_f32_e32 v65, v65
	v_sub_f32_e32 v66, v217, v191
	v_cvt_pk_bf16_f32 v63, v67, v68
	v_exp_f32_e32 v66, v66
	v_sub_f32_e32 v67, v218, v191
	v_exp_f32_e32 v67, v67
	v_add_f32_e32 v68, v64, v69
	v_sub_f32_e32 v69, v84, v191
	v_exp_f32_e32 v69, v69
	v_sub_f32_e32 v70, v85, v191
	v_add_f32_e32 v68, v65, v68
	v_exp_f32_e32 v70, v70
	v_sub_f32_e32 v71, v86, v191
	v_add_f32_e32 v68, v66, v68
	v_exp_f32_e32 v71, v71
	v_add_f32_e32 v68, v67, v68
	v_sub_f32_e32 v80, v87, v191
	v_exp_f32_e32 v80, v80
	v_add_f32_e32 v68, v69, v68
	v_cvt_pk_bf16_f32 v64, v64, v65
	v_cvt_pk_bf16_f32 v65, v66, v67
	v_cvt_pk_bf16_f32 v66, v69, v70
	v_sub_f32_e32 v69, v72, v191
	v_add_f32_e32 v68, v70, v68
	v_exp_f32_e32 v69, v69
	v_sub_f32_e32 v70, v73, v191
	v_add_f32_e32 v68, v71, v68
	v_cvt_pk_bf16_f32 v67, v71, v80
	v_exp_f32_e32 v70, v70
	v_sub_f32_e32 v71, v74, v191
	v_exp_f32_e32 v71, v71
	v_sub_f32_e32 v72, v75, v191
	v_add_f32_e32 v68, v80, v68
	v_exp_f32_e32 v72, v72
	v_sub_f32_e32 v73, v76, v191
	v_add_f32_e32 v68, v69, v68
	v_exp_f32_e32 v73, v73
	v_sub_f32_e32 v74, v77, v191
	v_add_f32_e32 v68, v70, v68
	v_exp_f32_e32 v74, v74
	v_sub_f32_e32 v75, v78, v191
	v_add_f32_e32 v68, v71, v68
	v_exp_f32_e32 v75, v75
	v_sub_f32_e32 v76, v79, v191
	v_add_f32_e32 v68, v72, v68
	v_exp_f32_e32 v76, v76
	v_add_f32_e32 v68, v73, v68
	v_add_f32_e32 v68, v74, v68
	v_add_f32_e32 v68, v75, v68
	v_add_f32_e32 v77, v76, v68
	v_cvt_pk_bf16_f32 v68, v69, v70
	v_cvt_pk_bf16_f32 v69, v71, v72
	v_sub_f32_e32 v72, v219, v191
	v_exp_f32_e32 v72, v72
	v_cvt_pk_bf16_f32 v70, v73, v74
	v_sub_f32_e32 v73, v220, v191
	v_exp_f32_e32 v73, v73
	v_sub_f32_e32 v74, v221, v191
	v_cvt_pk_bf16_f32 v71, v75, v76
	v_exp_f32_e32 v74, v74
	v_sub_f32_e32 v75, v223, v191
	v_exp_f32_e32 v75, v75
	v_add_f32_e32 v76, v72, v77
	v_sub_f32_e32 v77, v224, v191
	v_exp_f32_e32 v77, v77
	v_sub_f32_e32 v78, v225, v191
	v_add_f32_e32 v76, v73, v76
	v_exp_f32_e32 v78, v78
	v_sub_f32_e32 v79, v226, v191
	v_add_f32_e32 v76, v74, v76
	v_exp_f32_e32 v79, v79
	v_sub_f32_e32 v80, v227, v191
	v_add_f32_e32 v76, v75, v76
	v_exp_f32_e32 v80, v80
	v_add_f32_e32 v76, v77, v76
	v_cvt_pk_bf16_f32 v72, v72, v73
	v_cvt_pk_bf16_f32 v73, v74, v75
	v_cvt_pk_bf16_f32 v74, v77, v78
	v_sub_f32_e32 v77, v189, v191
	v_add_f32_e32 v76, v78, v76
	v_exp_f32_e32 v77, v77
	v_sub_f32_e32 v78, v228, v191
	v_add_f32_e32 v76, v79, v76
	v_cvt_pk_bf16_f32 v75, v79, v80
	v_exp_f32_e32 v78, v78
	v_sub_f32_e32 v79, v229, v191
	v_add_f32_e32 v76, v80, v76
	v_exp_f32_e32 v79, v79
	v_sub_f32_e32 v80, v230, v191
	v_exp_f32_e32 v80, v80
	v_sub_f32_e32 v81, v231, v191
	v_add_f32_e32 v76, v77, v76
	v_exp_f32_e32 v81, v81
	v_sub_f32_e32 v84, v232, v191
	v_add_f32_e32 v76, v78, v76
	v_exp_f32_e32 v84, v84
	v_sub_f32_e32 v85, v233, v191
	v_add_f32_e32 v76, v79, v76
	v_exp_f32_e32 v85, v85
	v_sub_f32_e32 v86, v234, v191
	v_add_f32_e32 v76, v80, v76
	v_exp_f32_e32 v86, v86
	v_add_f32_e32 v76, v81, v76
	v_add_f32_e32 v76, v84, v76
	v_add_f32_e32 v76, v85, v76
	v_add_f32_e32 v87, v86, v76
	ds_bpermute_b32 v88, v186, v87
	v_cvt_pk_bf16_f32 v76, v77, v78
	v_cvt_pk_bf16_f32 v77, v79, v80
	v_cvt_pk_bf16_f32 v78, v81, v84
	v_cvt_pk_bf16_f32 v79, v85, v86
	s_waitcnt lgkmcnt(0)
	v_add_f32_e32 v80, v87, v88
	ds_bpermute_b32 v81, v168, v80
	s_waitcnt vmcnt(0) lgkmcnt(0)
	s_barrier
; #define ATT_WAIT_BAR() do { asm volatile("s_waitcnt vmcnt(0) lgkmcnt(0)" ::: "memory"); __builtin_amdgcn_s_barrier(); asm volatile("" ::: "memory"); } while (0)
; __device__ __forceinline__ AttnUnit attn_decode(int un) {
;     AttnUnit u; const int bh = un >> 4, rc = (un >> 1) & 7; u.jh = un & 1; u.b = bh >> 3; u.h = bh & 7;
;     u.r0 = 8 * rc; u.krow_lo = rs_of(u.r0); u.nrows = rs_of(u.r0 + 7) + 8 - u.krow_lo;
;     return u;
; __device__ __forceinline__ void p2_attention(Frame& F, const bf16_t* Qg, const bf16_t* Kg, const bf16_t* Vg, bf16_t* MIX) {
;     ...
;             ATT_WAIT_BAR();
;             AttnUnit un = u; bf16x8 nq[2][2];
; #pragma unroll
;             for (int jb = 0; jb < 2; ++jb) { nq[jb][0] = qf[jb][0]; nq[jb][1] = qf[jb][1]; }
;             if (ui < UW - 1) {
;                 un = attn_decode(uidx + ui + 1);
;                 attn_dma<0>(lds0 + AT_A, Kg, un, wid, lane);
; #pragma unroll
;                 for (int jb = 0; jb < 2; ++jb) { const bf16_t* qp = Qg + ((size_t)(un.b * NHEAD + un.h) * SEQ + (un.r0 + wid) * 64 + 32 * un.jh + 16 * jb + q) * HD + 8 * g; nq[jb][0] = __builtin_nontemporal_load((const bf16x8*)qp); nq[jb][1] = __builtin_nontemporal_load((const bf16x8*)(qp + 32)); }
	s_cbranch_scc1 .LBB0_316
	s_add_i32 s0, s93, 9
	s_lshr_b32 s1, s0, 1
	s_xor_b32 s1, s1, s0
	s_and_b32 s1, s1, 1
	s_and_b32 s0, s0, 6
	s_or_b32 s1, s1, s0
	s_add_i32 s1, s1, s44
	s_lshl_b32 s90, s1, 2
	s_and_b32 s90, s90, 56
	v_sub_u32_e64 v188, s90, 4 clamp
	s_or_b32 s6, s90, 7
	s_min_u32 s6, s6, 60
	v_readfirstlane_b32 s8, v188
	s_ashr_i32 s0, s1, 7
	s_sub_i32 s6, s6, s8
	s_and_b32 s95, s1, 1
	s_lshl_b32 s101, s95, 4
	s_lshr_b32 s101, s100, s101
	s_bitcmp0_b32 s93, 0
	s_cselect_b32 s101, 0x3e0, s101
	s_bfe_u32 s1, s1, 0x30004
	s_add_i32 s91, s6, 4
	s_lshl_b32 s6, s0, 3
	s_or_b32 s6, s6, s1
	s_ashr_i32 s7, s6, 31
	s_lshl_b32 s8, s8, 6
	s_mul_i32 s9, s95, 24
	s_lshl_b64 s[6:7], s[6:7], 12
	s_or_b32 s8, s8, s9
	s_or_b32 s8, s6, s8
	s_mov_b32 s9, s7
	s_lshl_b64 s[8:9], s[8:9], 7
	s_add_u32 s8, s40, s8
	s_mul_i32 s10, s91, 5
	s_addc_u32 s9, s41, s9
	s_cmp_ge_i32 s85, s10
	s_cbranch_scc0 .LBB0_317
	s_cmp_ge_i32 s43, s10
	s_cbranch_scc0 .LBB0_318
